# all GEMM phases: small per-workgroup start offsets ((bid>>3)&3 x 0.2us) to de-phase K-step load bursts within an XCD
# baseline (speedup 1.0000x reference)
; __global__ void __launch_bounds__(NTHREADS, 2) fwd_kernel(Args A) {
;     ...
;         case 8: if (PMASK & 256) { pg8::Gemm g{(const bf16_t*)(ws + WS_U), wl + WT_F2, Mx, DM, DFF, MROWS, DM};        if (last) S.init(NLAT, DM, C.G, C.bid); else S.init(NLAT, DM, C.G, C.bid, NCTX, KSPLIT);
;                   pg8::EpiRes E{xs, xs + (size_t)NLAT * DM, last ? (float*)ARGP(C, 21) : xs, modl + 5 * DM, (float*)(ws + WS_PB)};
;                   pg8::gemm_phase<pg8::EpiRes, true>(C.lds, C.tid, g, S, E); } break;
.LBB0_88:
	v_writelane_b32 v248, s56, 7
	s_xor_b32 s16, s72, 7
	s_andn2_b64 vcc, exec, s[12:13]
	s_mov_b64 s[12:13], 0
	v_writelane_b32 v248, s92, 5
	s_cbranch_vccnz .LBB0_90
	v_readlane_b32 s12, v249, 57
	s_lshl_b32 s15, 0x120000, s16
	v_readlane_b32 s13, v249, 58
	s_and_b64 s[12:13], s[12:13], exec
	s_cselect_b32 s12, s15, 0x9000000
	s_mul_hi_u32 s13, s36, s12
	s_mul_i32 s12, s36, s12
.LBB0_90:
	v_readlane_b32 s100, v249, 56
	s_nop 3
	s_bfe_u32 s100, s100, 0x20003
	s_cmp_eq_u32 s100, 0
	s_cbranch_scc1 .Lff2off_nd
.Lff2off_d:
	s_sleep 6
	s_sub_u32 s100, s100, 1
	s_cmp_lg_u32 s100, 0
	s_cbranch_scc1 .Lff2off_d

;     __device__ bool next(int i, Unit& u) const {
;         const long L = (long)i * G + c;
;         if (L >= nwg) { const long j = L - nwg; if (j >= (long)nM2 * nN * nsplit) return false;
; __global__ void __launch_bounds__(NTHREADS, 2) fwd_kernel(Args A) {
;     ...
;         case 7: if (PMASK & 128) { pg8::Gemm g{H, wl + WT_F1, Mx, DFF, DM, 0, 0}; S.init(Mx, DFF, C.G, C.bid); pg8::EpiSq E{(bf16_t*)(ws + WS_U), DFF};
;                   pg8::gemm_phase<pg8::EpiSq, true>(C.lds, C.tid, g, S, E); } break;
.LBB0_133:
	s_andn2_b64 vcc, exec, s[0:1]
	s_cbranch_vccnz .LBB0_150
	s_lshr_b32 s36, s62, 3
	s_cmp_ge_i32 s51, s36
	v_readfirstlane_b32 s12, v208
	s_cbranch_scc1 .LBB0_150
	v_readlane_b32 s100, v249, 56
	s_nop 3
	s_bfe_u32 s100, s100, 0x20003
	s_cmp_eq_u32 s100, 0
	s_cbranch_scc1 .Lff1off_nd

; #define PG8_WAIT_V(n) asm volatile("s_waitcnt vmcnt(" #n ")" ::: "memory")
; #define PG8_BAR __builtin_amdgcn_s_barrier()
; template <class Epi, bool ALIGN_EPI>
; __device__ __forceinline__ void gemm_phase(LAS unsigned char* lds, const int tid, const Gemm g, const StaticOrder& S, const Epi& E) {
;     const int wid = __builtin_amdgcn_readfirstlane(tid >> 6), lane = tid & 63, wr = wid >> 2, wc = wid & 3, fr = lane & 15, fq = lane >> 4;
;     const int K = g.K, nt_full = K / BK, nt_split = S.nsplit > 0 ? nt_full / S.nsplit : nt_full;
;     const unsigned rsA = g.rowsA > 0 ? 128u : (unsigned)K * 2u, rsB = g.rowsB > 0 ? 128u : (unsigned)K * 2u;
;     const size_t kstepA = g.rowsA > 0 ? (size_t)g.rowsA * 128 : (size_t)(BK * 2), kstepB = g.rowsB > 0 ? (size_t)g.rowsB * 128 : (size_t)(BK * 2);
;     unsigned voffA[2], voffB[2];
; #pragma unroll
;     for (int i = 0; i < 2; ++i) { int R, C; stage_rc(tid * 16 + i * 8192, R, C); const int Rb = Epi::PERM ? ((R & ~31) + perm32(R & 31)) : R;
;         voffA[i] = (unsigned)R * rsA + (unsigned)C * 2u; voffB[i] = (unsigned)Rb * rsB + (unsigned)C * 2u; }
;     const size_t hstepA = (size_t)HALF * rsA, hstepB = (size_t)HALF * rsB;
;     const size_t tstepA = 2 * hstepA, tstepB = 2 * hstepB;
;     const unsigned ldsw = (unsigned)wid * 1024u;
;     const int aoff = lds_byte(wr * 64 + fr, fq * 8), boff = lds_byte(wc * 32 + fr, fq * 8);
;     ...
;     Unit cur, nxt; int ui = 0;
;     if (!S.next(0, cur)) return;
;     f32x4 acc[2][2][4][2];
; #pragma unroll
;     for (int a = 0; a < 2; ++a)
; #pragma unroll
;         for (int b = 0; b < 2; ++b)
; #pragma unroll
;             for (int m = 0; m < 4; ++m)
; #pragma unroll
;                 for (int n = 0; n < 2; ++n) acc[a][b][m][n] = (f32x4){0.f, 0.f, 0.f, 0.f};
;     bf16x8 At[4][2], B0[2][2], B1[2][2];
;     ...
;     const char* cA = (const char*)g.A + (size_t)cur.pm * tstepA + PG8_KOFFA(cur); const char* cB = (const char*)g.Bt + (size_t)cur.pn * tstepB + PG8_KOFFB(cur);
;     PG8_STAGE(PG8_SB(0, 0), cB, voffB); PG8_STAGE(PG8_SB(0, 1), cB + hstepB, voffB); PG8_STAGE(PG8_SA(0, 0), cA, voffA); PG8_STAGE(PG8_SA(0, 1), cA + hstepA, voffA);
;     if (wr == 1) PG8_BAR;
;     PG8_WAIT_V(2); PG8_BAR;
;     PG8_STAGE(PG8_SB(1, 0), cB + kstepB, voffB); PG8_STAGE(PG8_SA(1, 0), cA + kstepA, voffA); PG8_STAGE(PG8_SB(1, 1), cB + hstepB + kstepB, voffB);
;     PG8_WAIT_V(6); PG8_BAR;
.Lff1off_nd:
	v_lshlrev_b32_e32 v0, 4, v208
	v_add_u32_e32 v2, 0x2000, v0
	v_ashrrev_i32_e32 v3, 31, v2
	v_lshrrev_b32_e32 v3, 22, v3
	v_add_u32_e32 v3, v2, v3
	v_ashrrev_i32_e32 v10, 10, v3
	v_mul_i32_i24_e32 v3, 0x400, v10
	v_sub_u32_e32 v2, v2, v3
	v_lshrrev_b32_e32 v3, 4, v2
	v_bitop3_b32 v2, v3, v2, 32 bitop3:0x6c
	v_ashrrev_i32_e32 v3, 31, v2
	v_lshrrev_b32_e32 v3, 26, v3
	s_ashr_i32 s1, s12, 6
	v_add_u32_e32 v3, v2, v3
	v_lshlrev_b32_e32 v4, 3, v10
	s_ashr_i32 s13, s12, 8
	s_lshl_b32 s30, s1, 10
	v_readlane_b32 s0, v249, 59
	v_ashrrev_i32_e32 v11, 6, v3
	v_and_b32_e32 v4, -16, v4
	s_add_u32 s31, s0, 0x4100000
	v_readlane_b32 s0, v249, 60
	v_add_u32_e32 v4, v11, v4
	s_addc_u32 s34, s0, 0
	v_and_b32_e32 v5, 3, v11
	s_mov_b32 s0, 0xfffe0
	v_lshrrev_b32_e32 v6, 2, v4
	v_lshlrev_b32_e32 v7, 1, v4
	v_and_b32_e32 v3, 0xc0, v3
	v_and_or_b32 v5, v4, s0, v5
	v_and_b32_e32 v6, 4, v6
	v_and_b32_e32 v7, 24, v7
	v_sub_u32_e32 v2, v2, v3
	v_or3_b32 v5, v5, v6, v7
	v_lshlrev_b32_e32 v6, 5, v10
	v_ashrrev_i16_sdwa v2, v226, sext(v2) dst_sel:DWORD dst_unused:UNUSED_PAD src0_sel:DWORD src1_sel:BYTE_0
	v_and_b32_e32 v6, 32, v6
	v_bfe_i32 v12, v2, 0, 16
	v_add_lshl_u32 v2, v6, v12, 1
	v_lshl_add_u32 v130, v5, 12, v2
	v_lshl_add_u32 v132, v4, 12, v2
	v_bfe_i32 v2, v208, 27, 1
	v_lshrrev_b32_e32 v2, 22, v2
	v_add_u32_e32 v2, v0, v2
	v_and_b32_e32 v2, 0xfffffc00, v2
	v_sub_u32_e32 v0, v0, v2
	v_lshrrev_b32_e32 v2, 4, v0
	v_ashrrev_i32_e32 v3, 31, v208
	v_bitop3_b32 v0, v2, v0, 32 bitop3:0x6c
	v_lshrrev_b32_e32 v3, 26, v3
	v_ashrrev_i32_e32 v2, 31, v0
	v_add_u32_e32 v3, v208, v3
	v_lshrrev_b32_e32 v2, 26, v2
	v_ashrrev_i32_e32 v14, 6, v3
	v_add_u32_e32 v2, v0, v2
	v_lshlrev_b32_e32 v3, 3, v14
	v_ashrrev_i32_e32 v13, 6, v2
	v_and_b32_e32 v3, -16, v3
	v_add_u32_e32 v3, v13, v3
	v_and_b32_e32 v4, 3, v13
	s_ashr_i32 s47, s51, 31
	v_and_or_b32 v4, v3, s0, v4
	s_lshr_b32 s0, s47, 29
	s_add_i32 s0, s51, s0
	s_ashr_i32 s10, s0, 3
	s_and_b32 s0, s0, -8
	s_sub_i32 s0, s51, s0
	s_lshr_b32 s41, s62, 6
	s_lshr_b32 s11, s0, 31
	s_or_b32 s11, s41, s11
	s_mul_i32 s0, s0, s11
	s_add_i32 s0, s0, s10
	s_ashr_i32 s10, s0, 31
	s_lshr_b32 s10, s10, 24
	s_add_i32 s10, s0, s10
	v_lshrrev_b32_e32 v5, 2, v3
	v_lshlrev_b32_e32 v6, 1, v3
	v_and_b32_e32 v2, 0xc0, v2
	s_ashr_i32 s11, s10, 8
	s_lshr_b32 s35, s62, 8
	v_and_b32_e32 v5, 4, v5
	v_and_b32_e32 v6, 24, v6
	v_sub_u32_e32 v0, v0, v2
	s_lshl_b32 s14, s11, 3
	v_or3_b32 v4, v4, v5, v6
	v_lshlrev_b32_e32 v5, 5, v14
	v_ashrrev_i16_sdwa v0, v226, sext(v0) dst_sel:DWORD dst_unused:UNUSED_PAD src0_sel:DWORD src1_sel:BYTE_0
	s_sub_i32 s11, s35, s14
	v_and_b32_e32 v5, 32, v5
	v_bfe_i32 v15, v0, 0, 16
	s_min_u32 s15, s11, 8
	s_and_b32 s10, s10, 0xffffff00
	v_add_lshl_u32 v2, v5, v15, 1
	s_sub_i32 s16, s0, s10
	v_cvt_f32_ubyte0_e32 v5, s15
	v_lshl_add_u32 v0, v4, 12, v2
	v_cvt_f32_i32_e32 v4, s16
	v_rcp_iflag_f32_e32 v6, v5
	v_lshl_add_u32 v134, v3, 12, v2
	s_ashr_i32 s0, s16, 30
	s_or_b32 s0, s0, 1
	v_mul_f32_e32 v2, v4, v6
	v_trunc_f32_e32 v2, v2
	v_fma_f32 v3, -v2, v5, v4
	v_cvt_i32_f32_e32 v2, v2
	v_cmp_ge_f32_e64 s[10:11], |v3|, v5
	s_and_b64 s[10:11], s[10:11], exec
	s_cselect_b32 s0, s0, 0
	v_readfirstlane_b32 s10, v2
	s_add_i32 s0, s10, s0
	s_mul_i32 s10, s0, s15
	s_sub_i32 s10, s16, s10
	s_sext_i32_i16 s10, s10
	s_add_i32 s22, s14, s10
	s_ashr_i32 s23, s22, 31
	s_lshl_b64 s[10:11], s[22:23], 20
	v_readlane_b32 s14, v248, 4
	s_add_u32 s24, s14, s10
	v_readlane_b32 s10, v249, 63
	s_addc_u32 s25, s10, s11
	s_bfe_i64 s[10:11], s[0:1], 0x100000
	s_lshl_b64 s[10:11], s[10:11], 20
	s_add_u32 s26, s31, s10
	s_addc_u32 s27, s34, s11
	s_add_i32 s23, s30, 0
	s_add_i32 m0, s23, 0x10000
	v_mov_b32_e32 v131, v1
	global_load_lds_dwordx4 v0, s[26:27]
	s_add_i32 m0, s23, 0x12000
	s_add_u32 s10, s26, 0x80000
	global_load_lds_dwordx4 v130, s[26:27]
	s_addc_u32 s11, s27, 0
	s_add_i32 m0, s23, 0x14000
	s_add_i32 s52, s23, 0x2000
	global_load_lds_dwordx4 v0, s[10:11]
	s_add_i32 m0, s23, 0x16000
	v_mov_b32_e32 v135, v1
	global_load_lds_dwordx4 v130, s[10:11]
	s_mov_b32 m0, s23
	s_add_u32 s10, s24, 0x80000
	global_load_lds_dwordx4 v134, s[24:25]
	s_mov_b32 m0, s52
	s_addc_u32 s11, s25, 0
	s_add_i32 s54, s23, 0x4000
	global_load_lds_dwordx4 v132, s[24:25]
	s_mov_b32 m0, s54
	s_add_i32 s55, s23, 0x6000
	global_load_lds_dwordx4 v134, s[10:11]
	s_mov_b32 m0, s55
	v_mov_b32_e32 v133, v1
	global_load_lds_dwordx4 v132, s[10:11]
	s_cmp_eq_u32 s13, 1
	s_mov_b32 s71, s56
	v_lshl_add_u64 v[8:9], s[26:27], 0, v[0:1]
	v_lshl_add_u64 v[6:7], s[26:27], 0, v[130:131]
	v_lshl_add_u64 v[2:3], s[24:25], 0, v[134:135]
	s_cselect_b64 s[10:11], -1, 0
	s_cmp_lg_u32 s13, 1
	v_lshl_add_u64 v[4:5], s[24:25], 0, v[132:133]
	s_cbranch_scc1 .LBB0_137
	s_barrier

; __global__ void __launch_bounds__(NTHREADS, 2) fwd_kernel(Args A) {
;     ...
;         case 5: if (PMASK & 32) { pg8::Gemm g{(const bf16_t*)(ws + WS_MB), wl + WT_OUT, Mx, DM, DM, 0, 0}; if (last) S.init(NLAT, DM, C.G, C.bid); else S.init(NLAT, DM, C.G, C.bid, NCTX, KSPLIT);
;                   pg8::EpiRes E{last ? xs : ARGP(C, 0), last ? xs + (size_t)NLAT * DM : ARGP(C, 2), xs, modl + 2 * DM, (float*)(ws + WS_PB)};
;                   pg8::gemm_phase<pg8::EpiRes, true>(C.lds, C.tid, g, S, E); } break;
.LBB0_182:
	s_mov_b32 s81, s56
	s_mov_b32 s80, s92
	s_andn2_b64 vcc, exec, s[18:19]
	s_cbranch_vccnz .LBB0_184
	s_mov_b64 s[4:5], s[16:17]
.LBB0_184:
	v_readlane_b32 s100, v249, 56
	s_nop 3
	s_bfe_u32 s100, s100, 0x20003
	s_cmp_eq_u32 s100, 0
	s_cbranch_scc1 .Lwoutoff_nd

;     __device__ bool next(int i, Unit& u) const {
;     ...
;         int wgid = (int)L; { const int q = nwg / NXCD, r = nwg % NXCD, xcd = wgid % NXCD, off = wgid / NXCD; wgid = (xcd < r ? xcd * (q + 1) : r * (q + 1) + (xcd - r) * q) + off; }
; __global__ void __launch_bounds__(NTHREADS, 2) fwd_kernel(Args A) {
;     ...
;         case 1: if (PMASK & 2) { pg8::Gemm g{H, wl + WT_IN, MROWS, PROJ, DM, 0, 0}; S.init(MROWS, PROJ, C.G, C.bid); pg8::EpiIn E{(bf16_t*)(ws + WS_Z), (bf16_t*)(ws + WS_G), ARGP(C, 9) + (size_t)l * GW};
;                   pg8::gemm_phase<pg8::EpiIn, true>(C.lds, C.tid, g, S, E); } break;
.LBB0_653:
	s_andn2_b64 vcc, exec, s[0:1]
	s_cbranch_vccnz .LBB0_655
	s_mul_i32 s4, s9, 0xdd
.LBB0_655:
	v_readlane_b32 s100, v249, 56
	s_nop 3
	s_bfe_u32 s100, s100, 0x20003
	s_cmp_eq_u32 s100, 0
	s_cbranch_scc1 .Lwinoff_nd
